# MOD phase: sixteen adaLN weight loads of a k-group issued together instead of load/wait one at a time
# speedup vs baseline: 1.0071x; 1.0065x over previous
.LBB0_2962:
	v_add_co_u32_e32 v96, vcc, 0xfffd0000, v50
	v_addc_co_u32_e32 v97, vcc, -1, v51, vcc
	global_load_dword v64, v[96:97], off nt
	v_add_co_u32_e32 v96, vcc, 0xfffd6000, v50
	v_addc_co_u32_e32 v97, vcc, -1, v51, vcc
	global_load_dword v66, v[96:97], off nt
	v_add_co_u32_e32 v96, vcc, 0xfffdc000, v50
	v_addc_co_u32_e32 v97, vcc, -1, v51, vcc
	global_load_dword v68, v[96:97], off nt
	v_add_co_u32_e32 v96, vcc, 0xfffe2000, v50
	v_addc_co_u32_e32 v97, vcc, -1, v51, vcc
	global_load_dword v70, v[96:97], off nt
	v_add_co_u32_e32 v96, vcc, 0xfffe8000, v50
	v_addc_co_u32_e32 v97, vcc, -1, v51, vcc
	global_load_dword v72, v[96:97], off nt
	v_add_co_u32_e32 v96, vcc, 0xfffee000, v50
	v_addc_co_u32_e32 v97, vcc, -1, v51, vcc
	global_load_dword v74, v[96:97], off nt
	v_add_co_u32_e32 v96, vcc, 0xffff4000, v50
	v_addc_co_u32_e32 v97, vcc, -1, v51, vcc
	global_load_dword v76, v[96:97], off nt
	v_add_co_u32_e32 v96, vcc, 0xffffa000, v50
	v_addc_co_u32_e32 v97, vcc, -1, v51, vcc
	global_load_dword v78, v[96:97], off nt
	global_load_dword v80, v[50:51], off nt
	v_add_co_u32_e32 v96, vcc, 0x6000, v50
	v_addc_co_u32_e32 v97, vcc, 0, v51, vcc
	global_load_dword v82, v[96:97], off nt
	v_add_co_u32_e32 v96, vcc, 0xc000, v50
	v_addc_co_u32_e32 v97, vcc, 0, v51, vcc
	global_load_dword v84, v[96:97], off nt
	v_add_co_u32_e32 v96, vcc, 0x12000, v50
	v_addc_co_u32_e32 v97, vcc, 0, v51, vcc
	global_load_dword v86, v[96:97], off nt
	v_add_co_u32_e32 v96, vcc, 0x18000, v50
	v_addc_co_u32_e32 v97, vcc, 0, v51, vcc
	global_load_dword v88, v[96:97], off nt
	v_add_co_u32_e32 v96, vcc, 0x1e000, v50
	v_addc_co_u32_e32 v97, vcc, 0, v51, vcc
	global_load_dword v90, v[96:97], off nt
	v_add_co_u32_e32 v96, vcc, 0x24000, v50
	v_addc_co_u32_e32 v97, vcc, 0, v51, vcc
	global_load_dword v92, v[96:97], off nt
	v_add_co_u32_e32 v96, vcc, 0x2a000, v50
	v_addc_co_u32_e32 v97, vcc, 0, v51, vcc
	global_load_dword v94, v[96:97], off nt
	v_add_co_u32_e32 v0, vcc, 0xfffd0000, v50
	s_add_u32 s16, s10, s6
	s_nop 0
	v_addc_co_u32_e32 v1, vcc, -1, v51, vcc
	s_addc_u32 s17, s11, s7
	s_nop 0
	global_load_dwordx4 v[0:3], v153, s[16:17] offset:48
	global_load_dwordx4 v[12:15], v153, s[16:17] offset:32
	global_load_dwordx4 v[24:27], v153, s[16:17] offset:16
	global_load_dwordx4 v[36:39], v153, s[16:17]
	s_add_u32 s18, s16, 0x1000
	s_addc_u32 s19, s17, 0
	global_load_dwordx4 v[4:7], v153, s[18:19] offset:48
	global_load_dwordx4 v[16:19], v153, s[18:19] offset:32
	global_load_dwordx4 v[28:31], v153, s[18:19] offset:16
	global_load_dwordx4 v[40:43], v229, s[16:17]
	s_add_u32 s16, s8, s6
	s_addc_u32 s17, s9, s7
	global_load_dwordx4 v[8:11], v153, s[16:17] offset:48
	global_load_dwordx4 v[20:23], v153, s[16:17] offset:32
	global_load_dwordx4 v[32:35], v153, s[16:17] offset:16
	global_load_dwordx4 v[44:47], v153, s[16:17]
	s_mov_b32 s16, 0xfffd6000
	s_add_u32 s6, s6, 64
	s_addc_u32 s7, s7, 0
	s_cmpk_eq_i32 s6, 0x200
	s_waitcnt vmcnt(0)
	v_mul_f32_e32 v57, 0xbfb8aa3b, v36
	v_exp_f32_e32 v57, v57
	v_mov_b32_e32 v62, v36
	v_mov_b32_e32 v63, v40
	v_add_f32_e32 v57, 1.0, v57
	v_rcp_f32_e32 v60, v57
	v_mul_f32_e32 v57, 0xbfb8aa3b, v40
	v_mul_f32_e32 v36, 0xbfb8aa3b, v44
	v_exp_f32_e32 v57, v57
	v_exp_f32_e32 v36, v36
	v_mul_f32_e32 v40, 0xbfb8aa3b, v37
	v_exp_f32_e32 v40, v40
	v_add_f32_e32 v57, 1.0, v57
	v_add_f32_e32 v36, 1.0, v36
	v_rcp_f32_e32 v61, v57
	v_rcp_f32_e32 v36, v36
	v_add_f32_e32 v40, 1.0, v40
	v_pk_mul_f32 v[60:61], v[62:63], v[60:61]
	v_mul_f32_e32 v36, v44, v36
	v_pk_fma_f32 v[52:53], v[64:65], v[60:61], v[52:53] op_sel_hi:[0,1,1]
	v_fmac_f32_e32 v56, v64, v36
	v_add_co_u32_e32 v58, vcc, s16, v50
	s_mov_b32 s16, 0xfffdc000
	s_nop 0
	v_addc_co_u32_e32 v59, vcc, -1, v51, vcc
	v_rcp_f32_e32 v58, v40
	v_mul_f32_e32 v40, 0xbfb8aa3b, v41
	v_exp_f32_e32 v40, v40
	s_nop 0
	v_add_f32_e32 v40, 1.0, v40
	v_rcp_f32_e32 v59, v40
	v_mov_b32_e32 v40, v37
	v_pk_mul_f32 v[40:41], v[40:41], v[58:59]
	s_waitcnt vmcnt(0)
	v_pk_fma_f32 v[40:41], v[66:67], v[40:41], v[52:53] op_sel_hi:[0,1,1]
	v_mul_f32_e32 v37, 0xbfb8aa3b, v45
	v_exp_f32_e32 v37, v37
	v_mov_b32_e32 v52, v38
	v_mov_b32_e32 v53, v42
	v_add_f32_e32 v37, 1.0, v37
	v_rcp_f32_e32 v37, v37
	s_nop 0
	v_mul_f32_e32 v37, v45, v37
	v_fmac_f32_e32 v56, v66, v37
	v_add_co_u32_e32 v36, vcc, s16, v50
	s_mov_b32 s16, 0xfffe2000
	s_nop 0
	v_addc_co_u32_e32 v37, vcc, -1, v51, vcc
	v_mul_f32_e32 v37, 0xbfb8aa3b, v38
	v_exp_f32_e32 v37, v37
	s_nop 0
	v_add_f32_e32 v37, 1.0, v37
	v_rcp_f32_e32 v44, v37
	v_mul_f32_e32 v37, 0xbfb8aa3b, v42
	v_exp_f32_e32 v37, v37
	v_mov_b32_e32 v42, v39
	v_add_f32_e32 v37, 1.0, v37
	v_rcp_f32_e32 v45, v37
	s_nop 0
	v_pk_mul_f32 v[44:45], v[52:53], v[44:45]
	s_waitcnt vmcnt(0)
	v_pk_fma_f32 v[40:41], v[68:69], v[44:45], v[40:41] op_sel_hi:[0,1,1]
	v_mul_f32_e32 v37, 0xbfb8aa3b, v46
	v_exp_f32_e32 v37, v37
	s_nop 0
	v_add_f32_e32 v37, 1.0, v37
	v_rcp_f32_e32 v37, v37
	s_nop 0
	v_mul_f32_e32 v37, v46, v37
	v_fmac_f32_e32 v56, v68, v37
	v_add_co_u32_e32 v36, vcc, s16, v50
	s_mov_b32 s16, 0xfffe8000
	s_nop 0
	v_addc_co_u32_e32 v37, vcc, -1, v51, vcc
	v_mul_f32_e32 v37, 0xbfb8aa3b, v39
	v_exp_f32_e32 v37, v37
	s_nop 0
	v_add_f32_e32 v37, 1.0, v37
	v_rcp_f32_e32 v44, v37
	v_mul_f32_e32 v37, 0xbfb8aa3b, v43
	v_exp_f32_e32 v37, v37
	s_nop 0
	v_add_f32_e32 v37, 1.0, v37
	v_rcp_f32_e32 v45, v37
	s_nop 0
	v_pk_mul_f32 v[38:39], v[42:43], v[44:45]
	v_mov_b32_e32 v42, v24
	v_mov_b32_e32 v43, v28
	s_waitcnt vmcnt(0)
	v_pk_fma_f32 v[38:39], v[70:71], v[38:39], v[40:41] op_sel_hi:[0,1,1]
	v_mul_f32_e32 v37, 0xbfb8aa3b, v47
	v_exp_f32_e32 v37, v37
	s_nop 0
	v_add_f32_e32 v37, 1.0, v37
	v_rcp_f32_e32 v37, v37
	s_nop 0
	v_mul_f32_e32 v37, v47, v37
	v_fmac_f32_e32 v56, v70, v37
	v_add_co_u32_e32 v36, vcc, s16, v50
	s_mov_b32 s16, 0xfffee000
	s_nop 0
	v_addc_co_u32_e32 v37, vcc, -1, v51, vcc
	v_mul_f32_e32 v37, 0xbfb8aa3b, v24
	v_exp_f32_e32 v37, v37
	v_mul_f32_e32 v24, 0xbfb8aa3b, v32
	v_exp_f32_e32 v24, v24
	v_add_f32_e32 v37, 1.0, v37
	v_rcp_f32_e32 v40, v37
	v_mul_f32_e32 v37, 0xbfb8aa3b, v28
	v_exp_f32_e32 v37, v37
	v_add_f32_e32 v24, 1.0, v24
	v_rcp_f32_e32 v24, v24
	v_mul_f32_e32 v28, 0xbfb8aa3b, v25
	v_add_f32_e32 v37, 1.0, v37
	v_rcp_f32_e32 v41, v37
	v_mul_f32_e32 v24, v32, v24
	v_exp_f32_e32 v28, v28
	v_pk_mul_f32 v[40:41], v[42:43], v[40:41]
	v_add_f32_e32 v28, 1.0, v28
	s_waitcnt vmcnt(0)
	v_pk_fma_f32 v[38:39], v[72:73], v[40:41], v[38:39] op_sel_hi:[0,1,1]
	v_fmac_f32_e32 v56, v72, v24
	v_add_co_u32_e32 v36, vcc, s16, v50
	s_mov_b32 s16, 0xffff4000
	s_nop 0
	v_addc_co_u32_e32 v37, vcc, -1, v51, vcc
	v_rcp_f32_e32 v36, v28
	v_mul_f32_e32 v28, 0xbfb8aa3b, v29
	v_exp_f32_e32 v28, v28
	s_nop 0
	v_add_f32_e32 v28, 1.0, v28
	v_rcp_f32_e32 v37, v28
	v_mov_b32_e32 v28, v25
	v_pk_mul_f32 v[28:29], v[28:29], v[36:37]
	v_mov_b32_e32 v36, v26
	v_mov_b32_e32 v37, v30
	s_waitcnt vmcnt(0)
	v_pk_fma_f32 v[28:29], v[74:75], v[28:29], v[38:39] op_sel_hi:[0,1,1]
	v_mul_f32_e32 v25, 0xbfb8aa3b, v33
	v_exp_f32_e32 v25, v25
	s_nop 0
	v_add_f32_e32 v25, 1.0, v25
	v_rcp_f32_e32 v25, v25
	s_nop 0
	v_mul_f32_e32 v25, v33, v25
	v_fmac_f32_e32 v56, v74, v25
	v_add_co_u32_e32 v24, vcc, s16, v50
	s_movk_i32 s16, 0xa000
	s_nop 0
	v_addc_co_u32_e32 v25, vcc, -1, v51, vcc
	v_mul_f32_e32 v25, 0xbfb8aa3b, v26
	v_exp_f32_e32 v25, v25
	s_nop 0
	v_add_f32_e32 v25, 1.0, v25
	v_rcp_f32_e32 v32, v25
	v_mul_f32_e32 v25, 0xbfb8aa3b, v30
	v_exp_f32_e32 v25, v25
	v_mov_b32_e32 v30, v27
	v_add_f32_e32 v25, 1.0, v25
	v_rcp_f32_e32 v33, v25
	s_nop 0
	v_pk_mul_f32 v[32:33], v[36:37], v[32:33]
	s_waitcnt vmcnt(0)
	v_pk_fma_f32 v[28:29], v[76:77], v[32:33], v[28:29] op_sel_hi:[0,1,1]
	v_mul_f32_e32 v25, 0xbfb8aa3b, v34
	v_exp_f32_e32 v25, v25
	s_nop 0
	v_add_f32_e32 v25, 1.0, v25
	v_rcp_f32_e32 v25, v25
	s_nop 0
	v_mul_f32_e32 v25, v34, v25
	v_fmac_f32_e32 v56, v76, v25
	v_add_co_u32_e32 v24, vcc, s16, v50
	s_mov_b64 s[16:17], 0x60000
	s_nop 0
	v_addc_co_u32_e32 v25, vcc, -1, v51, vcc
	v_mul_f32_e32 v25, 0xbfb8aa3b, v27
	v_exp_f32_e32 v25, v25
	s_nop 0
	v_add_f32_e32 v25, 1.0, v25
	v_rcp_f32_e32 v32, v25
	v_mul_f32_e32 v25, 0xbfb8aa3b, v31
	v_exp_f32_e32 v25, v25
	s_nop 0
	v_add_f32_e32 v25, 1.0, v25
	v_rcp_f32_e32 v33, v25
	s_nop 0
	v_pk_mul_f32 v[26:27], v[30:31], v[32:33]
	v_mov_b32_e32 v30, v12
	v_mov_b32_e32 v31, v16
	s_waitcnt vmcnt(0)
	v_pk_fma_f32 v[26:27], v[78:79], v[26:27], v[28:29] op_sel_hi:[0,1,1]
	v_mul_f32_e32 v25, 0xbfb8aa3b, v35
	v_exp_f32_e32 v25, v25
	s_nop 0
	v_add_f32_e32 v25, 1.0, v25
	v_rcp_f32_e32 v25, v25
	s_nop 0
	v_mul_f32_e32 v25, v35, v25
	v_fmac_f32_e32 v56, v78, v25
	v_mul_f32_e32 v25, 0xbfb8aa3b, v12
	v_exp_f32_e32 v25, v25
	v_mul_f32_e32 v12, 0xbfb8aa3b, v20
	v_exp_f32_e32 v12, v12
	v_add_f32_e32 v25, 1.0, v25
	v_rcp_f32_e32 v28, v25
	v_mul_f32_e32 v25, 0xbfb8aa3b, v16
	v_exp_f32_e32 v25, v25
	v_add_f32_e32 v12, 1.0, v12
	v_rcp_f32_e32 v12, v12
	v_mul_f32_e32 v16, 0xbfb8aa3b, v13
	v_add_f32_e32 v25, 1.0, v25
	v_rcp_f32_e32 v29, v25
	v_mul_f32_e32 v12, v20, v12
	v_exp_f32_e32 v16, v16
	v_pk_mul_f32 v[28:29], v[30:31], v[28:29]
	v_add_f32_e32 v16, 1.0, v16
	s_waitcnt vmcnt(0)
	v_pk_fma_f32 v[26:27], v[80:81], v[28:29], v[26:27] op_sel_hi:[0,1,1]
	v_fmac_f32_e32 v56, v80, v12
	v_add_co_u32_e32 v24, vcc, s69, v50
	s_nop 1
	v_addc_co_u32_e32 v25, vcc, 0, v51, vcc
	v_rcp_f32_e32 v24, v16
	v_mul_f32_e32 v16, 0xbfb8aa3b, v17
	v_exp_f32_e32 v16, v16
	s_nop 0
	v_add_f32_e32 v16, 1.0, v16
	v_rcp_f32_e32 v25, v16
	v_mov_b32_e32 v16, v13
	v_pk_mul_f32 v[16:17], v[16:17], v[24:25]
	v_mov_b32_e32 v24, v14
	v_mov_b32_e32 v25, v18
	s_waitcnt vmcnt(0)
	v_pk_fma_f32 v[16:17], v[82:83], v[16:17], v[26:27] op_sel_hi:[0,1,1]
	v_mul_f32_e32 v13, 0xbfb8aa3b, v21
	v_exp_f32_e32 v13, v13
	s_nop 0
	v_add_f32_e32 v13, 1.0, v13
	v_rcp_f32_e32 v13, v13
	s_nop 0
	v_mul_f32_e32 v13, v21, v13
	v_fmac_f32_e32 v56, v82, v13
	v_add_co_u32_e32 v12, vcc, s75, v50
	s_nop 1
	v_addc_co_u32_e32 v13, vcc, 0, v51, vcc
	v_mul_f32_e32 v13, 0xbfb8aa3b, v14
	v_exp_f32_e32 v13, v13
	s_nop 0
	v_add_f32_e32 v13, 1.0, v13
	v_rcp_f32_e32 v20, v13
	v_mul_f32_e32 v13, 0xbfb8aa3b, v18
	v_exp_f32_e32 v13, v13
	v_mov_b32_e32 v18, v15
	v_add_f32_e32 v13, 1.0, v13
	v_rcp_f32_e32 v21, v13
	s_nop 0
	v_pk_mul_f32 v[20:21], v[24:25], v[20:21]
	s_waitcnt vmcnt(0)
	v_pk_fma_f32 v[16:17], v[84:85], v[20:21], v[16:17] op_sel_hi:[0,1,1]
	v_mul_f32_e32 v13, 0xbfb8aa3b, v22
	v_exp_f32_e32 v13, v13
	s_nop 0
	v_add_f32_e32 v13, 1.0, v13
	v_rcp_f32_e32 v13, v13
	s_nop 0
	v_mul_f32_e32 v13, v22, v13
	v_fmac_f32_e32 v56, v84, v13
	v_add_co_u32_e32 v12, vcc, s74, v50
	s_nop 1
	v_addc_co_u32_e32 v13, vcc, 0, v51, vcc
	v_mul_f32_e32 v13, 0xbfb8aa3b, v15
	v_exp_f32_e32 v13, v13
	s_nop 0
	v_add_f32_e32 v13, 1.0, v13
	v_rcp_f32_e32 v20, v13
	v_mul_f32_e32 v13, 0xbfb8aa3b, v19
	v_exp_f32_e32 v13, v13
	s_nop 0
	v_add_f32_e32 v13, 1.0, v13
	v_rcp_f32_e32 v21, v13
	s_nop 0
	v_pk_mul_f32 v[14:15], v[18:19], v[20:21]
	v_mov_b32_e32 v18, v0
	v_mov_b32_e32 v19, v4
	s_waitcnt vmcnt(0)
	v_pk_fma_f32 v[14:15], v[86:87], v[14:15], v[16:17] op_sel_hi:[0,1,1]
	v_mul_f32_e32 v13, 0xbfb8aa3b, v23
	v_exp_f32_e32 v13, v13
	s_nop 0
	v_add_f32_e32 v13, 1.0, v13
	v_rcp_f32_e32 v13, v13
	s_nop 0
	v_mul_f32_e32 v13, v23, v13
	v_fmac_f32_e32 v56, v86, v13
	v_add_co_u32_e32 v12, vcc, s70, v50
	s_nop 1
	v_addc_co_u32_e32 v13, vcc, 0, v51, vcc
	v_mul_f32_e32 v13, 0xbfb8aa3b, v0
	v_exp_f32_e32 v13, v13
	v_mul_f32_e32 v0, 0xbfb8aa3b, v8
	v_exp_f32_e32 v0, v0
	v_add_f32_e32 v13, 1.0, v13
	v_rcp_f32_e32 v16, v13
	v_mul_f32_e32 v13, 0xbfb8aa3b, v4
	v_exp_f32_e32 v13, v13
	v_add_f32_e32 v0, 1.0, v0
	v_rcp_f32_e32 v0, v0
	v_mul_f32_e32 v4, 0xbfb8aa3b, v1
	v_add_f32_e32 v13, 1.0, v13
	v_rcp_f32_e32 v17, v13
	v_mul_f32_e32 v0, v8, v0
	v_exp_f32_e32 v4, v4
	v_pk_mul_f32 v[16:17], v[18:19], v[16:17]
	v_add_f32_e32 v4, 1.0, v4
	s_waitcnt vmcnt(0)
	v_pk_fma_f32 v[14:15], v[88:89], v[16:17], v[14:15] op_sel_hi:[0,1,1]
	v_fmac_f32_e32 v56, v88, v0
	v_add_co_u32_e32 v12, vcc, s87, v50
	s_nop 1
	v_addc_co_u32_e32 v13, vcc, 0, v51, vcc
	v_rcp_f32_e32 v12, v4
	v_mul_f32_e32 v4, 0xbfb8aa3b, v5
	v_exp_f32_e32 v4, v4
	s_nop 0
	v_add_f32_e32 v4, 1.0, v4
	v_rcp_f32_e32 v13, v4
	v_mov_b32_e32 v4, v1
	v_pk_mul_f32 v[4:5], v[4:5], v[12:13]
	v_mov_b32_e32 v12, v2
	v_mov_b32_e32 v13, v6
	s_waitcnt vmcnt(0)
	v_pk_fma_f32 v[4:5], v[90:91], v[4:5], v[14:15] op_sel_hi:[0,1,1]
	v_mul_f32_e32 v1, 0xbfb8aa3b, v9
	v_exp_f32_e32 v1, v1
	s_nop 0
	v_add_f32_e32 v1, 1.0, v1
	v_rcp_f32_e32 v1, v1
	s_nop 0
	v_mul_f32_e32 v1, v9, v1
	v_fmac_f32_e32 v56, v90, v1
	v_add_co_u32_e32 v0, vcc, s52, v50
	s_nop 1
	v_addc_co_u32_e32 v1, vcc, 0, v51, vcc
	v_mul_f32_e32 v1, 0xbfb8aa3b, v2
	v_exp_f32_e32 v1, v1
	s_nop 0
	v_add_f32_e32 v1, 1.0, v1
	v_rcp_f32_e32 v8, v1
	v_mul_f32_e32 v1, 0xbfb8aa3b, v6
	v_exp_f32_e32 v1, v1
	v_mov_b32_e32 v6, v3
	v_add_f32_e32 v1, 1.0, v1
	v_rcp_f32_e32 v9, v1
	s_nop 0
	v_pk_mul_f32 v[8:9], v[12:13], v[8:9]
	s_waitcnt vmcnt(0)
	v_pk_fma_f32 v[4:5], v[92:93], v[8:9], v[4:5] op_sel_hi:[0,1,1]
	v_mul_f32_e32 v1, 0xbfb8aa3b, v10
	v_exp_f32_e32 v1, v1
	s_nop 0
	v_add_f32_e32 v1, 1.0, v1
	v_rcp_f32_e32 v1, v1
	s_nop 0
	v_mul_f32_e32 v1, v10, v1
	v_fmac_f32_e32 v56, v92, v1
	v_add_co_u32_e32 v0, vcc, s20, v50
	s_nop 1
	v_addc_co_u32_e32 v1, vcc, 0, v51, vcc
	v_mul_f32_e32 v1, 0xbfb8aa3b, v3
	v_exp_f32_e32 v1, v1
	v_lshl_add_u64 v[50:51], v[50:51], 0, s[16:17]
	v_add_f32_e32 v1, 1.0, v1
	v_rcp_f32_e32 v8, v1
	v_mul_f32_e32 v1, 0xbfb8aa3b, v7
	v_exp_f32_e32 v1, v1
	s_nop 0
	v_add_f32_e32 v1, 1.0, v1
	v_rcp_f32_e32 v9, v1
	s_nop 0
	v_pk_mul_f32 v[2:3], v[6:7], v[8:9]
	s_waitcnt vmcnt(0)
	v_pk_fma_f32 v[52:53], v[94:95], v[2:3], v[4:5] op_sel_hi:[0,1,1]
	v_mul_f32_e32 v1, 0xbfb8aa3b, v11
	v_exp_f32_e32 v1, v1
	s_nop 0
	v_add_f32_e32 v1, 1.0, v1
	v_rcp_f32_e32 v1, v1
	s_nop 0
	v_mul_f32_e32 v1, v11, v1
	v_fmac_f32_e32 v56, v94, v1
	s_cbranch_scc0 .LBB0_2962
	s_andn2_b64 vcc, exec, s[4:5]
	ds_write2st64_b32 v54, v52, v53 offset1:1
	ds_write_b32 v54, v56 offset:512
	s_waitcnt lgkmcnt(0)
	s_barrier
	s_cbranch_vccnz .LBB0_2960
	s_mul_i32 s6, s15, 0x1800
	v_add_u32_e32 v0, s6, v48
	v_ashrrev_i32_e32 v1, 31, v0
	v_lshl_add_u64 v[0:1], v[0:1], 2, s[0:1]
	global_load_dword v20, v[0:1], off
	ds_read2st64_b32 v[4:5], v55 offset1:1
	ds_read2st64_b32 v[6:7], v55 offset0:2 offset1:3
	ds_read2st64_b32 v[8:9], v55 offset0:6 offset1:7
	ds_read2st64_b32 v[10:11], v55 offset0:8 offset1:9
	ds_read2st64_b32 v[12:13], v55 offset0:12 offset1:13
	ds_read2st64_b32 v[14:15], v55 offset0:14 offset1:15
	ds_read2st64_b32 v[16:17], v55 offset0:18 offset1:19
	ds_read2st64_b32 v[18:19], v55 offset0:20 offset1:21
	s_waitcnt lgkmcnt(7)
	v_add_f32_e32 v4, 0, v4
	s_waitcnt lgkmcnt(6)
	v_add_f32_e32 v4, v4, v7
	s_waitcnt lgkmcnt(5)
	v_add_f32_e32 v4, v4, v8
	s_waitcnt lgkmcnt(4)
	v_add_f32_e32 v4, v4, v11
	s_waitcnt lgkmcnt(3)
	v_add_f32_e32 v4, v4, v12
	s_waitcnt lgkmcnt(2)
	v_add_f32_e32 v4, v4, v15
	s_waitcnt lgkmcnt(1)
	v_add_f32_e32 v4, v4, v16
	v_lshl_add_u64 v[2:3], v[48:49], 2, s[2:3]
	v_mov_b32_e32 v21, 0x12000
	s_waitcnt lgkmcnt(0)
	v_add_f32_e32 v4, v4, v19
	v_mad_i64_i32 v[2:3], s[6:7], s15, v21, v[2:3]
	v_add_f32_e32 v5, 0, v5
	v_add_co_u32_e32 v28, vcc, s69, v2
	s_waitcnt vmcnt(0)
	v_add_f32_e32 v4, v4, v20
	global_store_dword v[2:3], v4, off
	global_load_dword v4, v[0:1], off
	ds_read2st64_b32 v[20:21], v55 offset0:4 offset1:5
	ds_read2st64_b32 v[22:23], v55 offset0:10 offset1:11
	ds_read2st64_b32 v[24:25], v55 offset0:22 offset1:23
	ds_read2st64_b32 v[26:27], v55 offset0:16 offset1:17
	v_addc_co_u32_e32 v29, vcc, 0, v3, vcc
	s_waitcnt lgkmcnt(3)
	v_add_f32_e32 v5, v5, v20
	v_add_f32_e32 v5, v5, v9
	s_waitcnt lgkmcnt(2)
	v_add_f32_e32 v5, v5, v22
	v_add_f32_e32 v5, v5, v13
	s_waitcnt lgkmcnt(0)
	v_add_f32_e32 v5, v5, v26
	v_add_f32_e32 v5, v5, v17
	v_add_f32_e32 v5, v5, v24
	s_waitcnt vmcnt(0)
	v_add_f32_e32 v4, v5, v4
	global_store_dword v[28:29], v4, off
	global_load_dword v1, v[0:1], off
	v_add_co_u32_e32 v0, vcc, 0xc000, v2
	v_add_f32_e32 v2, 0, v6
	v_add_f32_e32 v2, v2, v21
	v_add_f32_e32 v2, v2, v10
	v_add_f32_e32 v2, v2, v23
	v_add_f32_e32 v2, v2, v14
	v_add_f32_e32 v2, v2, v27
	v_add_f32_e32 v2, v2, v18
	v_add_f32_e32 v2, v2, v25
	s_waitcnt vmcnt(0)
	v_add_f32_e32 v2, v2, v1
	v_addc_co_u32_e32 v1, vcc, 0, v3, vcc
	global_store_dword v[0:1], v2, off
	s_branch .LBB0_2960
